# P5 near key blocks: per-element bias address math (add+clamp+shift-add x32) replaced by immediate offsets from one base, clip handled by 63 extra table entries
# baseline (speedup 1.0000x reference)
; #define LAS __attribute__((address_space(3)))
; __device__ __forceinline__ void attn_wave(LAS unsigned char* wl, const bf16* Q, const bf16* K, const bf16* V, bf16* O, const float* relb, int b, int n, int h, int lane) {
;     ...
;     LAS float* biasL = (LAS float*)(wl + 6144);
;     for (int i = lane; i < 257; i += 64) biasL[i] = relb[h * 257 + i] * 1.4426950408889634f;
;     const size_t tq0 = (size_t)b * SEQ + (size_t)n * 64;
;     bf16x8 qf[2][4];
; #pragma unroll
;     for (int qb = 0; qb < 2; ++qb)
; #pragma unroll
;         for (int ks = 0; ks < 4; ++ks) qf[qb][ks] = *(const bf16x8*)(Q + (tq0 + 32 * qb + r32) * AW + h * 64 + 16 * ks + 8 * hf);
;     f32x16 o[2][2];
; #pragma unroll
;     for (int db = 0; db < 2; ++db)
; #pragma unroll
;         for (int qb = 0; qb < 2; ++qb)
; #pragma unroll
;             for (int i = 0; i < 16; ++i) o[db][qb][i] = 0.f;
;     float mrun[2] = {-INFINITY, -INFINITY}, lrun[2] = {0.f, 0.f};
;     const float CL2 = 0.125f * 1.4426950408889634f;
;     const int kk0 = n >= 8 ? 0 : 2 * (8 - n);
;     const bf16* kp = K + ((size_t)b * SEQ + (size_t)(n - 8) * 64 + r32) * AW + h * 64 + 8 * hf;
;     const bf16* vp = V + ((size_t)b * SEQ + (size_t)(n - 8) * 64 + (lane >> 3)) * AW + h * 64 + 8 * (lane & 7);
;     bf16x8 kf[4]; v4u vr[4];
; #pragma unroll
;     for (int ks = 0; ks < 4; ++ks) kf[ks] = *(const bf16x8*)(kp + (size_t)kk0 * 32 * AW + 16 * ks);
; #pragma unroll
;     for (int i = 0; i < 4; ++i) vr[i] = *(const v4u*)(vp + ((size_t)kk0 * 32 + 8 * i) * AW);
.LBB0_553:
	s_or_b64 exec, exec, s[0:1]
	v_mov_b32_e32 v253, s53
	ds_read_b32 v254, v253 offset:7168
	v_mbcnt_lo_u32_b32 v255, -1, 0
	v_mbcnt_hi_u32_b32 v255, -1, v255
	v_lshl_add_u32 v255, v255, 2, s53
	s_waitcnt lgkmcnt(0)
	ds_write_b32 v255, v254 offset:7172
	s_lshl_b32 s0, s80, 5
	s_and_b32 s0, s0, 0xe0
	s_ashr_i32 s1, s80, 3
	s_add_i32 s0, s0, s1
	s_ashr_i32 s1, s0, 31
	s_lshr_b32 s1, s1, 25
	s_add_i32 s1, s0, s1
	s_ashr_i32 s14, s1, 7
	s_and_b32 s1, s1, 0xffffff80
	s_sub_i32 s16, s0, s1
	s_ashr_i32 s15, s14, 31
	s_ashr_i32 s17, s16, 31
	s_lshl_b64 s[0:1], s[14:15], 13
	s_lshl_b64 s[18:19], s[16:17], 6
	s_add_u32 s17, s18, s0
	s_addc_u32 s20, s19, s1
	s_lshl_b32 s21, s16, 1
	s_sub_i32 s21, 16, s21
	s_cmp_lt_i32 s16, 8
	v_mov_b32_e32 v1, s20
	v_or_b32_e32 v0, s17, v164
	s_cselect_b32 s44, s21, 0
	v_lshlrev_b64 v[186:187], 10, v[0:1]
	v_mov_b32_e32 v189, 0
	s_cmp_lt_i32 s44, 18
	v_mov_b32_e32 v188, 0
	v_mov_b32_e32 v63, 0
	v_mov_b32_e32 v62, 0
	v_mov_b32_e32 v61, 0
	v_mov_b32_e32 v60, 0
	v_mov_b32_e32 v59, 0
	v_mov_b32_e32 v58, 0
	v_mov_b32_e32 v57, 0
	v_mov_b32_e32 v56, 0
	v_mov_b32_e32 v55, 0
	v_mov_b32_e32 v54, 0
	v_mov_b32_e32 v53, 0
	v_mov_b32_e32 v52, 0
	v_mov_b32_e32 v51, 0
	v_mov_b32_e32 v50, 0
	v_mov_b32_e32 v49, 0
	v_mov_b32_e32 v48, 0
	v_mov_b32_e32 v31, 0
	v_mov_b32_e32 v30, 0
	v_mov_b32_e32 v29, 0
	v_mov_b32_e32 v28, 0
	v_mov_b32_e32 v27, 0
	v_mov_b32_e32 v26, 0
	v_mov_b32_e32 v25, 0
	v_mov_b32_e32 v24, 0
	v_mov_b32_e32 v23, 0
	v_mov_b32_e32 v22, 0
	v_mov_b32_e32 v21, 0
	v_mov_b32_e32 v20, 0
	v_mov_b32_e32 v19, 0
	v_mov_b32_e32 v18, 0
	v_mov_b32_e32 v17, 0
	v_mov_b32_e32 v16, 0
	v_mov_b32_e32 v47, 0
	v_mov_b32_e32 v46, 0
	v_mov_b32_e32 v45, 0
	v_mov_b32_e32 v44, 0
	v_mov_b32_e32 v43, 0
	v_mov_b32_e32 v42, 0
	v_mov_b32_e32 v41, 0
	v_mov_b32_e32 v40, 0
	v_mov_b32_e32 v39, 0
	v_mov_b32_e32 v38, 0
	v_mov_b32_e32 v37, 0
	v_mov_b32_e32 v36, 0
	v_mov_b32_e32 v35, 0
	v_mov_b32_e32 v34, 0
	v_mov_b32_e32 v33, 0
	v_mov_b32_e32 v32, 0
	v_mov_b32_e32 v15, 0
	v_mov_b32_e32 v14, 0
	v_mov_b32_e32 v13, 0
	v_mov_b32_e32 v12, 0
	v_mov_b32_e32 v11, 0
	v_mov_b32_e32 v10, 0
	v_mov_b32_e32 v9, 0
	v_mov_b32_e32 v8, 0
	v_mov_b32_e32 v7, 0
	v_mov_b32_e32 v6, 0
	v_mov_b32_e32 v5, 0
	v_mov_b32_e32 v4, 0
	v_mov_b32_e32 v3, 0
	v_mov_b32_e32 v2, 0
	v_mov_b32_e32 v1, 0
	v_mov_b32_e32 v0, 0
	s_cbranch_scc0 .LBB0_564
	v_lshl_add_u64 v[0:1], v[166:167], 0, v[186:187]
	s_add_u32 s0, s18, s0
	global_load_dwordx4 v[96:99], v[0:1], off
	global_load_dwordx4 v[100:103], v[0:1], off offset:32
	global_load_dwordx4 v[104:107], v[0:1], off offset:64
	global_load_dwordx4 v[108:111], v[0:1], off offset:96
	v_mov_b32_e32 v1, s20
	v_or_b32_e32 v0, s17, v170
	s_addc_u32 s1, s19, s1
	v_lshlrev_b64 v[0:1], 10, v[0:1]
	s_add_u32 s0, s0, 0xfffffe00
	v_lshl_add_u64 v[0:1], v[166:167], 0, v[0:1]
	s_addc_u32 s1, s1, -1
	global_load_dwordx4 v[112:115], v[0:1], off
	global_load_dwordx4 v[116:119], v[0:1], off offset:32
	global_load_dwordx4 v[120:123], v[0:1], off offset:64
	global_load_dwordx4 v[124:127], v[0:1], off offset:96
	v_mov_b32_e32 v1, s1
	v_or_b32_e32 v0, s0, v164
	v_lshlrev_b64 v[0:1], 10, v[0:1]
	v_lshl_add_u64 v[190:191], v[172:173], 0, v[0:1]
	v_lshl_add_u64 v[0:1], s[0:1], 0, v[174:175]
	v_lshlrev_b64 v[0:1], 10, v[0:1]
	v_lshl_add_u64 v[192:193], v[176:177], 0, v[0:1]
	s_lshl_b64 s[0:1], s[44:45], 15
	v_lshl_add_u64 v[0:1], v[192:193], 0, s[0:1]
	v_add_co_u32_e32 v2, vcc, s75, v0
	v_mov_b32_e32 v14, v168
	s_nop 0
	v_addc_co_u32_e32 v3, vcc, 0, v1, vcc
	v_add_co_u32_e32 v4, vcc, s76, v0
	v_mov_b32_e32 v15, v168
	s_nop 0
	v_addc_co_u32_e32 v5, vcc, 0, v1, vcc
	v_add_co_u32_e32 v6, vcc, s77, v0
	v_mov_b32_e32 v169, v168
	s_nop 0
	v_addc_co_u32_e32 v7, vcc, 0, v1, vcc
	global_load_dwordx4 v[152:155], v[4:5], off
	global_load_dwordx4 v[148:151], v[6:7], off
	global_load_dwordx4 v[156:159], v[2:3], off
	global_load_dwordx4 v[144:147], v[0:1], off
	v_lshl_add_u64 v[0:1], v[190:191], 0, s[0:1]
	global_load_dwordx4 v[128:131], v[0:1], off offset:96
	global_load_dwordx4 v[132:135], v[0:1], off offset:64
	global_load_dwordx4 v[136:139], v[0:1], off offset:32
	global_load_dwordx4 v[140:143], v[0:1], off
	v_and_b32_e32 v1, 64, v233
	v_xor_b32_e32 v0, 32, v233
	v_add_u32_e32 v1, 64, v1
	v_cmp_lt_i32_e32 vcc, v0, v1
	s_lshl_b32 s0, s44, 5
	v_mov_b32_e32 v1, v168
	v_cndmask_b32_e32 v0, v233, v0, vcc
	v_lshlrev_b32_e32 v234, 2, v0
	v_mov_b32_e32 v0, v168
	v_mov_b32_e32 v2, v168
	v_mov_b32_e32 v3, v168
	v_mov_b32_e32 v4, v168
	v_mov_b32_e32 v5, v168
	v_mov_b32_e32 v6, v168
	v_mov_b32_e32 v7, v168
	v_mov_b32_e32 v8, v168
	v_mov_b32_e32 v9, v168
	v_mov_b32_e32 v10, v168
	v_mov_b32_e32 v11, v168
	v_mov_b32_e32 v12, v168
	v_mov_b32_e32 v13, v168
	v_mov_b64_e32 v[46:47], v[14:15]
	v_mov_b64_e32 v[30:31], v[14:15]
	v_mov_b64_e32 v[62:63], v[14:15]
	v_subrev_u32_e32 v235, s0, v230
	s_add_i32 s17, s44, -1
	v_mov_b32_e32 v236, 0xff800000
	v_mov_b64_e32 v[44:45], v[12:13]
	v_mov_b64_e32 v[42:43], v[10:11]
	v_mov_b64_e32 v[40:41], v[8:9]
	v_mov_b64_e32 v[38:39], v[6:7]
	v_mov_b64_e32 v[36:37], v[4:5]
	v_mov_b64_e32 v[34:35], v[2:3]
	v_mov_b64_e32 v[32:33], v[0:1]
	v_mov_b64_e32 v[28:29], v[12:13]
	v_mov_b64_e32 v[26:27], v[10:11]
	v_mov_b64_e32 v[24:25], v[8:9]
	v_mov_b64_e32 v[22:23], v[6:7]
	v_mov_b64_e32 v[20:21], v[4:5]
	v_mov_b64_e32 v[18:19], v[2:3]
	v_mov_b64_e32 v[16:17], v[0:1]
	v_mov_b64_e32 v[60:61], v[12:13]
	v_mov_b64_e32 v[58:59], v[10:11]
	v_mov_b64_e32 v[56:57], v[8:9]
	v_mov_b64_e32 v[54:55], v[6:7]
	v_mov_b64_e32 v[52:53], v[4:5]
	v_mov_b64_e32 v[50:51], v[2:3]
	v_mov_b64_e32 v[48:49], v[0:1]
	v_mov_b32_e32 v237, 0xff800000
	v_mov_b64_e32 v[188:189], v[168:169]
	s_branch .LBB0_556

; __device__ __forceinline__ void attn_wave(LAS unsigned char* wl, const bf16* Q, const bf16* K, const bf16* V, bf16* O, const float* relb, int b, int n, int h, int lane) {
;     ...
;         if (kk < 12) {
;             const float cb = biasL[256];
; #pragma unroll
;             for (int qb = 0; qb < 2; ++qb) { float m_ = -INFINITY;
; #pragma unroll
;                 for (int i = 0; i < 16; ++i) { const float val = s[qb][i] * CL2 + cb; s[qb][i] = val; m_ = fmaxf(m_, val); }
;                 mx[qb] = m_; }
;         } else {
; #pragma unroll
;             for (int qb = 0; qb < 2; ++qb) { float m_ = -INFINITY;
; #pragma unroll
;                 for (int i = 0; i < 16; ++i) {
;                     int dist = dbase + 32 * qb - (8 * (i >> 2) + (i & 3)); dist = dist > 128 ? 128 : dist;
;                     const float val = s[qb][i] * CL2 + biasL[dist + 128];
;                     s[qb][i] = val; m_ = fmaxf(m_, val);
;                 }
;                 mx[qb] = m_; }
.LBB0_558:
	s_add_i32 s17, s17, 1
	s_cmp_lt_i32 s17, 12
	s_mov_b64 s[0:1], -1
	s_cbranch_scc1 .LBB0_560
	v_lshl_add_u32 v253, v235, 2, s53
	ds_read_b32 v194, v253 offset:6764
	ds_read_b32 v195, v253 offset:6760
	ds_read_b32 v196, v253 offset:6756
	ds_read_b32 v197, v253 offset:6752
	ds_read_b32 v198, v253 offset:6732
	ds_read_b32 v199, v253 offset:6728
	ds_read_b32 v200, v253 offset:6724
	ds_read_b32 v201, v253 offset:6720
	ds_read_b32 v202, v253 offset:6700
	ds_read_b32 v203, v253 offset:6696
	ds_read_b32 v206, v253 offset:6692
	ds_read_b32 v207, v253 offset:6688
	ds_read_b32 v208, v253 offset:6668
	ds_read_b32 v209, v253 offset:6664
	ds_read_b32 v210, v253 offset:6660
	ds_read_b32 v211, v253 offset:6656
	s_waitcnt lgkmcnt(6)
	v_pk_fma_f32 v[204:205], v[88:89], s[56:57], v[202:203] op_sel_hi:[1,0,1]
	ds_read_b32 v202, v253 offset:6892
	ds_read_b32 v203, v253 offset:6888
	ds_read_b32 v212, v253 offset:6884
	ds_read_b32 v213, v253 offset:6880
	ds_read_b32 v214, v253 offset:6860
	ds_read_b32 v215, v253 offset:6856
	ds_read_b32 v216, v253 offset:6852
	ds_read_b32 v217, v253 offset:6848
	s_waitcnt lgkmcnt(6)
	v_pk_fma_f32 v[220:221], v[64:65], s[56:57], v[202:203] op_sel_hi:[1,0,1]
	s_waitcnt lgkmcnt(4)
	v_pk_fma_f32 v[222:223], v[66:67], s[56:57], v[212:213] op_sel_hi:[1,0,1]
	v_max3_f32 v202, v220, s78, v221
	v_max3_f32 v202, v202, v222, v223
	s_waitcnt lgkmcnt(2)
	v_pk_fma_f32 v[224:225], v[68:69], s[56:57], v[214:215] op_sel_hi:[1,0,1]
	v_max3_f32 v212, v202, v224, v225
	s_waitcnt lgkmcnt(0)
	v_pk_fma_f32 v[202:203], v[70:71], s[56:57], v[216:217] op_sel_hi:[1,0,1]
	v_max3_f32 v240, v212, v202, v203
	v_pk_fma_f32 v[194:195], v[80:81], s[56:57], v[194:195] op_sel_hi:[1,0,1]
	v_max3_f32 v169, v194, s78, v195
	v_pk_fma_f32 v[196:197], v[82:83], s[56:57], v[196:197] op_sel_hi:[1,0,1]
	v_max3_f32 v169, v169, v196, v197
	v_pk_fma_f32 v[198:199], v[84:85], s[56:57], v[198:199] op_sel_hi:[1,0,1]
	ds_read_b32 v212, v253 offset:6828
	ds_read_b32 v213, v253 offset:6824
	ds_read_b32 v214, v253 offset:6820
	ds_read_b32 v215, v253 offset:6816
	ds_read_b32 v216, v253 offset:6796
	ds_read_b32 v217, v253 offset:6792
	ds_read_b32 v238, v253 offset:6788
	ds_read_b32 v239, v253 offset:6784
	v_max3_f32 v169, v169, v198, v199
	v_pk_fma_f32 v[200:201], v[86:87], s[56:57], v[200:201] op_sel_hi:[1,0,1]
	s_waitcnt lgkmcnt(6)
	v_pk_fma_f32 v[218:219], v[72:73], s[56:57], v[212:213] op_sel_hi:[1,0,1]
	v_max3_f32 v169, v169, v200, v201
	v_max3_f32 v169, v169, v204, v205
	v_pk_fma_f32 v[206:207], v[90:91], s[56:57], v[206:207] op_sel_hi:[1,0,1]
	v_max3_f32 v212, v240, v218, v219
	s_waitcnt lgkmcnt(4)
	v_pk_fma_f32 v[214:215], v[74:75], s[56:57], v[214:215] op_sel_hi:[1,0,1]
	v_max3_f32 v169, v169, v206, v207
	v_pk_fma_f32 v[208:209], v[92:93], s[56:57], v[208:209] op_sel_hi:[1,0,1]
	v_max3_f32 v240, v212, v214, v215
	s_waitcnt lgkmcnt(2)
	v_pk_fma_f32 v[212:213], v[76:77], s[56:57], v[216:217] op_sel_hi:[1,0,1]
	v_max3_f32 v169, v169, v208, v209
	v_pk_fma_f32 v[210:211], v[94:95], s[56:57], v[210:211] op_sel_hi:[1,0,1]
	v_max3_f32 v240, v240, v212, v213
	s_waitcnt lgkmcnt(0)
	v_pk_fma_f32 v[216:217], v[78:79], s[56:57], v[238:239] op_sel_hi:[1,0,1]
	v_max3_f32 v169, v169, v210, v211
	v_max3_f32 v238, v240, v216, v217
	s_cbranch_execz .LBB0_561
	s_branch .LBB0_562

; __global__ void __launch_bounds__(512, 2) hybrid_fwd(Args args) {
	.amdhsa_kernel _Z10hybrid_fwd4Args
		.amdhsa_group_segment_fixed_size 0
		.amdhsa_private_segment_fixed_size 0
		.amdhsa_kernarg_size 440
		.amdhsa_user_sgpr_count 2
		.amdhsa_user_sgpr_dispatch_ptr 0
		.amdhsa_user_sgpr_queue_ptr 0
		.amdhsa_user_sgpr_kernarg_segment_ptr 1
		.amdhsa_user_sgpr_dispatch_id 0
		.amdhsa_user_sgpr_kernarg_preload_length 0
		.amdhsa_user_sgpr_kernarg_preload_offset 0
		.amdhsa_user_sgpr_private_segment_size 0
		.amdhsa_uses_dynamic_stack 0
		.amdhsa_enable_private_segment 0
		.amdhsa_system_sgpr_workgroup_id_x 1
		.amdhsa_system_sgpr_workgroup_id_y 0
		.amdhsa_system_sgpr_workgroup_id_z 0
		.amdhsa_system_sgpr_workgroup_info 0
		.amdhsa_system_vgpr_workitem_id 2
		.amdhsa_next_free_vgpr 256
		.amdhsa_next_free_sgpr 102
		.amdhsa_accum_offset 256
		.amdhsa_reserve_vcc 1
		.amdhsa_float_round_mode_32 0
		.amdhsa_float_round_mode_16_64 0
		.amdhsa_float_denorm_mode_32 3
		.amdhsa_float_denorm_mode_16_64 3
		.amdhsa_dx10_clamp 1
		.amdhsa_ieee_mode 1
		.amdhsa_fp16_overflow 0
		.amdhsa_tg_split 0
		.amdhsa_exception_fp_ieee_invalid_op 0
		.amdhsa_exception_fp_denorm_src 0
		.amdhsa_exception_fp_ieee_div_zero 0
		.amdhsa_exception_fp_ieee_overflow 0
		.amdhsa_exception_fp_ieee_underflow 0
		.amdhsa_exception_fp_ieee_inexact 0
		.amdhsa_exception_int_div_zero 0
	.end_amdhsa_kernel

; __global__ void __launch_bounds__(512, 2) hybrid_fwd(Args args) {
amdhsa.kernels:
  - .agpr_count:     0
    .args:
      - .offset:         0
        .size:           184
        .value_kind:     by_value
      - .offset:         184
        .size:           4
        .value_kind:     hidden_block_count_x
      - .offset:         188
        .size:           4
        .value_kind:     hidden_block_count_y
      - .offset:         192
        .size:           4
        .value_kind:     hidden_block_count_z
      - .offset:         196
        .size:           2
        .value_kind:     hidden_group_size_x
      - .offset:         198
        .size:           2
        .value_kind:     hidden_group_size_y
      - .offset:         200
        .size:           2
        .value_kind:     hidden_group_size_z
      - .offset:         202
        .size:           2
        .value_kind:     hidden_remainder_x
      - .offset:         204
        .size:           2
        .value_kind:     hidden_remainder_y
      - .offset:         206
        .size:           2
        .value_kind:     hidden_remainder_z
      - .offset:         224
        .size:           8
        .value_kind:     hidden_global_offset_x
      - .offset:         232
        .size:           8
        .value_kind:     hidden_global_offset_y
      - .offset:         240
        .size:           8
        .value_kind:     hidden_global_offset_z
      - .offset:         248
        .size:           2
        .value_kind:     hidden_grid_dims
      - .offset:         272
        .size:           8
        .value_kind:     hidden_multigrid_sync_arg
      - .offset:         304
        .size:           4
        .value_kind:     hidden_dynamic_lds_size
    .group_segment_fixed_size: 0
    .kernarg_segment_align: 8
    .kernarg_segment_size: 440
    .language:       OpenCL C
    .language_version:
      - 2
      - 0
    .max_flat_workgroup_size: 512
    .name:           _Z10hybrid_fwd4Args
    .private_segment_fixed_size: 0
    .sgpr_count:     108
    .sgpr_spill_count: 13
    .symbol:         _Z10hybrid_fwd4Args.kd
    .uniform_work_group_size: 1
    .uses_dynamic_stack: false
    .vgpr_count:     256
    .vgpr_spill_count: 0
    .wavefront_size: 64
